# GLU GEMM epilogue: the 15 serialized z loads hoisted to the epilogue top into free registers, per-step vmcnt(15) instead of vmcnt(0)
# baseline (speedup 1.0000x reference)
.LBB0_1519:
	v_lshl_add_u32 v154, s36, 8, v162
	v_ashrrev_i32_e32 v155, 31, v154
	v_lshl_add_u64 v[16:17], v[154:155], 2, s[12:13]
	global_load_dwordx4 v[32:35], v[16:17], off offset:16
	global_load_dwordx4 v[36:39], v[16:17], off
	global_load_dwordx4 v[20:23], v[16:17], off offset:528
	s_nop 0
	global_load_dwordx4 v[16:19], v[16:17], off offset:512
	v_lshl_add_u32 v156, s86, 8, v160
	v_ashrrev_i32_e32 v157, 31, v156
	v_lshlrev_b64 v[158:159], 10, v[156:157]
	v_lshl_add_u64 v[158:159], s[8:9], 0, v[158:159]
	v_lshlrev_b64 v[154:155], 1, v[154:155]
	v_lshl_add_u64 v[158:159], v[158:159], 0, v[154:155]
	global_load_dwordx4 v[164:167], v[158:159], off
	global_load_dwordx4 v[176:179], v[158:159], off offset:256
	v_add_u32_e32 v170, 0x10, v156
	v_ashrrev_i32_e32 v171, 31, v170
	v_lshlrev_b64 v[230:231], 10, v[170:171]
	v_lshl_add_u64 v[230:231], s[8:9], 0, v[230:231]
	v_lshl_add_u64 v[230:231], v[230:231], 0, v[154:155]
	global_load_dwordx4 v[180:183], v[230:231], off
	global_load_dwordx4 v[184:187], v[230:231], off offset:256
	v_add_u32_e32 v170, 0x20, v156
	v_ashrrev_i32_e32 v171, 31, v170
	v_lshlrev_b64 v[230:231], 10, v[170:171]
	v_lshl_add_u64 v[230:231], s[8:9], 0, v[230:231]
	v_lshl_add_u64 v[230:231], v[230:231], 0, v[154:155]
	global_load_dwordx4 v[188:191], v[230:231], off
	global_load_dwordx4 v[192:195], v[230:231], off offset:256
	v_add_u32_e32 v170, 0x30, v156
	v_ashrrev_i32_e32 v171, 31, v170
	v_lshlrev_b64 v[230:231], 10, v[170:171]
	v_lshl_add_u64 v[230:231], s[8:9], 0, v[230:231]
	v_lshl_add_u64 v[230:231], v[230:231], 0, v[154:155]
	global_load_dwordx4 v[196:199], v[230:231], off
	global_load_dwordx4 v[200:203], v[230:231], off offset:256
	v_add_u32_e32 v170, 0x80, v156
	v_ashrrev_i32_e32 v171, 31, v170
	v_lshlrev_b64 v[230:231], 10, v[170:171]
	v_lshl_add_u64 v[230:231], s[8:9], 0, v[230:231]
	v_lshl_add_u64 v[230:231], v[230:231], 0, v[154:155]
	global_load_dwordx4 v[204:207], v[230:231], off
	global_load_dwordx4 v[208:211], v[230:231], off offset:256
	v_add_u32_e32 v170, 0x90, v156
	v_ashrrev_i32_e32 v171, 31, v170
	v_lshlrev_b64 v[230:231], 10, v[170:171]
	v_lshl_add_u64 v[230:231], s[8:9], 0, v[230:231]
	v_lshl_add_u64 v[230:231], v[230:231], 0, v[154:155]
	global_load_dwordx4 v[212:215], v[230:231], off
	global_load_dwordx4 v[218:221], v[230:231], off offset:256
	v_add_u32_e32 v170, 0xa0, v156
	v_ashrrev_i32_e32 v171, 31, v170
	v_lshlrev_b64 v[230:231], 10, v[170:171]
	v_lshl_add_u64 v[230:231], s[8:9], 0, v[230:231]
	v_lshl_add_u64 v[230:231], v[230:231], 0, v[154:155]
	global_load_dwordx4 v[222:225], v[230:231], off
	global_load_dwordx4 v[226:229], v[230:231], off offset:256
	v_add_u32_e32 v170, 0xb0, v156
	v_ashrrev_i32_e32 v171, 31, v170
	v_lshlrev_b64 v[230:231], 10, v[170:171]
	v_lshl_add_u64 v[230:231], s[8:9], 0, v[230:231]
	v_lshl_add_u64 v[230:231], v[230:231], 0, v[154:155]
	global_load_dwordx4 v[242:245], v[230:231], off
	global_load_dwordx4 v[250:253], v[230:231], off offset:256
	s_mov_b64 s[52:53], -1
	s_andn2_b64 vcc, exec, s[4:5]
	s_waitcnt vmcnt(15)
	v_pk_add_f32 v[136:137], v[136:137], v[32:33]
	v_pk_add_f32 v[140:141], v[140:141], v[36:37]
	v_pk_add_f32 v[142:143], v[142:143], v[38:39]
	v_mul_f32_e32 v141, 0xbfb8aa3b, v141
	v_exp_f32_e32 v141, v141
	v_mul_f32_e32 v142, 0xbfb8aa3b, v142
	v_exp_f32_e32 v142, v142
	v_mul_f32_e32 v136, 0xbfb8aa3b, v136
	v_exp_f32_e32 v136, v136
	v_add_f32_e32 v141, 1.0, v141
	v_rcp_f32_e32 v141, v141
	v_add_f32_e32 v142, 1.0, v142
	v_rcp_f32_e32 v142, v142
	v_add_f32_e32 v136, 1.0, v136
	v_rcp_f32_e32 v136, v136
	v_lshlrev_b32_e32 v168, 16, v164
	v_and_b32_e32 v164, 0xffff0000, v164
	v_mul_f32_e32 v141, v141, v164
	v_lshlrev_b32_e32 v164, 16, v165
	v_mul_f32_e32 v142, v142, v164
	v_mul_f32_e32 v143, 0xbfb8aa3b, v143
	v_lshlrev_b32_e32 v164, 16, v166
	v_pk_add_f32 v[138:139], v[138:139], v[34:35]
	v_exp_f32_e32 v143, v143
	v_mul_f32_e32 v164, v136, v164
	v_mul_f32_e32 v136, 0xbfb8aa3b, v137
	v_exp_f32_e32 v136, v136
	v_mul_f32_e32 v138, 0xbfb8aa3b, v138
	v_exp_f32_e32 v138, v138
	v_add_f32_e32 v143, 1.0, v143
	v_rcp_f32_e32 v143, v143
	v_add_f32_e32 v136, 1.0, v136
	v_rcp_f32_e32 v136, v136
	v_add_f32_e32 v138, 1.0, v138
	v_rcp_f32_e32 v138, v138
	v_and_b32_e32 v165, 0xffff0000, v165
	v_mul_f32_e32 v143, v143, v165
	v_and_b32_e32 v165, 0xffff0000, v166
	v_mul_f32_e32 v140, 0xbfb8aa3b, v140
	v_mul_f32_e32 v165, v136, v165
	v_lshlrev_b32_e32 v136, 16, v167
	v_exp_f32_e32 v140, v140
	v_mul_f32_e32 v166, v138, v136
	v_mul_f32_e32 v136, 0xbfb8aa3b, v139
	v_exp_f32_e32 v136, v136
	v_add_f32_e32 v140, 1.0, v140
	v_rcp_f32_e32 v140, v140
	v_and_b32_e32 v137, 0xffff0000, v167
	v_add_f32_e32 v136, 1.0, v136
	v_rcp_f32_e32 v136, v136
	v_mul_f32_e32 v140, v140, v168
	v_pk_add_f32 v[132:133], v[132:133], v[16:17]
	v_pk_add_f32 v[134:135], v[134:135], v[18:19]
	v_mul_f32_e32 v139, v136, v137
	v_cvt_pk_bf16_f32 v136, v140, v141
	v_lshlrev_b64 v[140:141], 12, v[156:157]
	v_lshl_add_u64 v[140:141], s[10:11], 0, v[140:141]
	v_lshl_add_u64 v[140:141], v[140:141], 0, v[154:155]
	v_cvt_pk_bf16_f32 v137, v142, v143
	v_cvt_pk_bf16_f32 v138, v164, v165
	v_cvt_pk_bf16_f32 v139, v166, v139
	global_store_dwordx4 v[140:141], v[136:139], off offset:2048
	v_mul_f32_e32 v133, 0xbfb8aa3b, v133
	v_pk_add_f32 v[128:129], v[128:129], v[20:21]
	v_exp_f32_e32 v133, v133
	v_mul_f32_e32 v134, 0xbfb8aa3b, v134
	v_exp_f32_e32 v134, v134
	v_mul_f32_e32 v128, 0xbfb8aa3b, v128
	v_exp_f32_e32 v128, v128
	v_add_f32_e32 v133, 1.0, v133
	v_rcp_f32_e32 v133, v133
	v_add_f32_e32 v134, 1.0, v134
	v_rcp_f32_e32 v134, v134
	v_add_f32_e32 v128, 1.0, v128
	v_rcp_f32_e32 v128, v128
	v_mul_f32_e32 v135, 0xbfb8aa3b, v135
	v_pk_add_f32 v[130:131], v[130:131], v[22:23]
	v_exp_f32_e32 v135, v135
	v_mul_f32_e32 v130, 0xbfb8aa3b, v130
	v_exp_f32_e32 v130, v130
	v_mul_f32_e32 v132, 0xbfb8aa3b, v132
	v_add_f32_e32 v135, 1.0, v135
	v_rcp_f32_e32 v135, v135
	v_add_f32_e32 v130, 1.0, v130
	v_rcp_f32_e32 v130, v130
	v_exp_f32_e32 v132, v132
	v_pk_add_f32 v[124:125], v[124:125], v[36:37]
	v_pk_add_f32 v[126:127], v[126:127], v[38:39]
	v_mul_f32_e32 v125, 0xbfb8aa3b, v125
	v_add_f32_e32 v132, 1.0, v132
	v_rcp_f32_e32 v132, v132
	v_pk_add_f32 v[120:121], v[120:121], v[32:33]
	v_exp_f32_e32 v125, v125
	v_mul_f32_e32 v126, 0xbfb8aa3b, v126
	v_exp_f32_e32 v126, v126
	v_mul_f32_e32 v120, 0xbfb8aa3b, v120
	v_exp_f32_e32 v120, v120
	v_add_f32_e32 v125, 1.0, v125
	v_rcp_f32_e32 v125, v125
	v_add_f32_e32 v126, 1.0, v126
	v_rcp_f32_e32 v126, v126
	v_add_f32_e32 v120, 1.0, v120
	v_rcp_f32_e32 v120, v120
	v_mul_f32_e32 v127, 0xbfb8aa3b, v127
	v_pk_add_f32 v[122:123], v[122:123], v[34:35]
	v_exp_f32_e32 v127, v127
	v_mul_f32_e32 v122, 0xbfb8aa3b, v122
	v_exp_f32_e32 v122, v122
	v_mul_f32_e32 v124, 0xbfb8aa3b, v124
	v_add_f32_e32 v127, 1.0, v127
	v_rcp_f32_e32 v127, v127
	v_add_f32_e32 v122, 1.0, v122
	v_rcp_f32_e32 v122, v122
	v_exp_f32_e32 v124, v124
	v_pk_add_f32 v[116:117], v[116:117], v[16:17]
	v_pk_add_f32 v[118:119], v[118:119], v[18:19]
	v_mul_f32_e32 v117, 0xbfb8aa3b, v117
	v_add_f32_e32 v124, 1.0, v124
	v_rcp_f32_e32 v124, v124
	v_pk_add_f32 v[112:113], v[112:113], v[20:21]
	v_exp_f32_e32 v117, v117
	v_mul_f32_e32 v118, 0xbfb8aa3b, v118
	v_exp_f32_e32 v118, v118
	v_mul_f32_e32 v112, 0xbfb8aa3b, v112
	v_exp_f32_e32 v112, v112
	v_add_f32_e32 v117, 1.0, v117
	v_rcp_f32_e32 v117, v117
	v_add_f32_e32 v118, 1.0, v118
	v_rcp_f32_e32 v118, v118
	v_add_f32_e32 v112, 1.0, v112
	v_rcp_f32_e32 v112, v112
	v_mul_f32_e32 v119, 0xbfb8aa3b, v119
	v_pk_add_f32 v[114:115], v[114:115], v[22:23]
	v_exp_f32_e32 v119, v119
	v_mul_f32_e32 v114, 0xbfb8aa3b, v114
	v_exp_f32_e32 v114, v114
	v_mul_f32_e32 v116, 0xbfb8aa3b, v116
	v_add_f32_e32 v119, 1.0, v119
	v_rcp_f32_e32 v119, v119
	v_add_f32_e32 v114, 1.0, v114
	v_rcp_f32_e32 v114, v114
	s_waitcnt vmcnt(15)
	v_lshlrev_b32_e32 v142, 16, v176
	v_and_b32_e32 v136, 0xffff0000, v176
	v_mul_f32_e32 v133, v133, v136
	v_lshlrev_b32_e32 v136, 16, v177
	v_mul_f32_e32 v134, v134, v136
	v_lshlrev_b32_e32 v136, 16, v178
	v_mul_f32_e32 v136, v128, v136
	v_mul_f32_e32 v128, 0xbfb8aa3b, v129
	v_exp_f32_e32 v128, v128
	v_and_b32_e32 v137, 0xffff0000, v177
	v_mul_f32_e32 v135, v135, v137
	v_and_b32_e32 v137, 0xffff0000, v178
	v_add_f32_e32 v128, 1.0, v128
	v_rcp_f32_e32 v128, v128
	v_and_b32_e32 v129, 0xffff0000, v179
	v_mul_f32_e32 v132, v132, v142
	v_exp_f32_e32 v116, v116
	v_mul_f32_e32 v137, v128, v137
	v_lshlrev_b32_e32 v128, 16, v179
	v_mul_f32_e32 v138, v130, v128
	v_mul_f32_e32 v128, 0xbfb8aa3b, v131
	v_exp_f32_e32 v128, v128
	v_add_f32_e32 v116, 1.0, v116
	v_rcp_f32_e32 v116, v116
	v_pk_add_f32 v[108:109], v[108:109], v[36:37]
	v_add_f32_e32 v128, 1.0, v128
	v_rcp_f32_e32 v128, v128
	v_pk_add_f32 v[110:111], v[110:111], v[38:39]
	v_mul_f32_e32 v109, 0xbfb8aa3b, v109
	v_pk_add_f32 v[104:105], v[104:105], v[32:33]
	v_mul_f32_e32 v131, v128, v129
	v_cvt_pk_bf16_f32 v128, v132, v133
	v_cvt_pk_bf16_f32 v129, v134, v135
	v_cvt_pk_bf16_f32 v130, v136, v137
	v_cvt_pk_bf16_f32 v131, v138, v131
	global_store_dwordx4 v[140:141], v[128:131], off offset:2304
	v_exp_f32_e32 v109, v109
	v_mul_f32_e32 v110, 0xbfb8aa3b, v110
	v_or_b32_e32 v130, 16, v156
	v_ashrrev_i32_e32 v131, 31, v130
	v_lshlrev_b64 v[128:129], 10, v[130:131]
	v_lshl_add_u64 v[128:129], s[8:9], 0, v[128:129]
	v_lshl_add_u64 v[128:129], v[128:129], 0, v[154:155]
	v_exp_f32_e32 v110, v110
	v_mul_f32_e32 v104, 0xbfb8aa3b, v104
	v_exp_f32_e32 v104, v104
	v_add_f32_e32 v109, 1.0, v109
	v_rcp_f32_e32 v109, v109
	v_add_f32_e32 v110, 1.0, v110
	v_rcp_f32_e32 v110, v110
	v_add_f32_e32 v104, 1.0, v104
	v_rcp_f32_e32 v104, v104
	v_mul_f32_e32 v111, 0xbfb8aa3b, v111
	v_pk_add_f32 v[106:107], v[106:107], v[34:35]
	v_exp_f32_e32 v111, v111
	v_mul_f32_e32 v106, 0xbfb8aa3b, v106
	v_exp_f32_e32 v106, v106
	v_mul_f32_e32 v108, 0xbfb8aa3b, v108
	v_add_f32_e32 v111, 1.0, v111
	v_rcp_f32_e32 v111, v111
	v_add_f32_e32 v106, 1.0, v106
	v_rcp_f32_e32 v106, v106
	v_exp_f32_e32 v108, v108
	v_pk_add_f32 v[100:101], v[100:101], v[16:17]
	v_pk_add_f32 v[102:103], v[102:103], v[18:19]
	v_mul_f32_e32 v101, 0xbfb8aa3b, v101
	v_add_f32_e32 v108, 1.0, v108
	v_rcp_f32_e32 v108, v108
	v_pk_add_f32 v[96:97], v[96:97], v[20:21]
	v_exp_f32_e32 v101, v101
	v_mul_f32_e32 v102, 0xbfb8aa3b, v102
	v_exp_f32_e32 v102, v102
	v_mul_f32_e32 v96, 0xbfb8aa3b, v96
	v_exp_f32_e32 v96, v96
	v_add_f32_e32 v101, 1.0, v101
	v_rcp_f32_e32 v101, v101
	v_add_f32_e32 v102, 1.0, v102
	v_rcp_f32_e32 v102, v102
	v_add_f32_e32 v96, 1.0, v96
	v_rcp_f32_e32 v96, v96
	v_mul_f32_e32 v103, 0xbfb8aa3b, v103
	v_pk_add_f32 v[98:99], v[98:99], v[22:23]
	v_exp_f32_e32 v103, v103
	v_mul_f32_e32 v98, 0xbfb8aa3b, v98
	v_exp_f32_e32 v98, v98
	v_mul_f32_e32 v100, 0xbfb8aa3b, v100
	v_add_f32_e32 v103, 1.0, v103
	v_rcp_f32_e32 v103, v103
	v_add_f32_e32 v98, 1.0, v98
	v_rcp_f32_e32 v98, v98
	v_exp_f32_e32 v100, v100
	v_pk_add_f32 v[92:93], v[92:93], v[36:37]
	v_pk_add_f32 v[94:95], v[94:95], v[38:39]
	v_mul_f32_e32 v93, 0xbfb8aa3b, v93
	v_add_f32_e32 v100, 1.0, v100
	v_rcp_f32_e32 v100, v100
	v_pk_add_f32 v[88:89], v[88:89], v[32:33]
	v_exp_f32_e32 v93, v93
	v_mul_f32_e32 v94, 0xbfb8aa3b, v94
	v_exp_f32_e32 v94, v94
	v_mul_f32_e32 v88, 0xbfb8aa3b, v88
	v_exp_f32_e32 v88, v88
	v_add_f32_e32 v93, 1.0, v93
	v_rcp_f32_e32 v93, v93
	v_add_f32_e32 v94, 1.0, v94
	v_rcp_f32_e32 v94, v94
	v_add_f32_e32 v88, 1.0, v88
	v_rcp_f32_e32 v88, v88
	v_mul_f32_e32 v95, 0xbfb8aa3b, v95
	v_pk_add_f32 v[90:91], v[90:91], v[34:35]
	v_exp_f32_e32 v95, v95
	v_mul_f32_e32 v90, 0xbfb8aa3b, v90
	v_exp_f32_e32 v90, v90
	v_mul_f32_e32 v92, 0xbfb8aa3b, v92
	v_add_f32_e32 v95, 1.0, v95
	v_rcp_f32_e32 v95, v95
	v_add_f32_e32 v90, 1.0, v90
	v_rcp_f32_e32 v90, v90
	v_exp_f32_e32 v92, v92
	v_pk_add_f32 v[84:85], v[84:85], v[16:17]
	v_pk_add_f32 v[86:87], v[86:87], v[18:19]
	v_mul_f32_e32 v85, 0xbfb8aa3b, v85
	s_waitcnt vmcnt(15)
	v_lshlrev_b32_e32 v136, 16, v180
	v_and_b32_e32 v132, 0xffff0000, v180
	v_mul_f32_e32 v125, v125, v132
	v_lshlrev_b32_e32 v132, 16, v181
	v_mul_f32_e32 v126, v126, v132
	v_lshlrev_b32_e32 v132, 16, v182
	v_mul_f32_e32 v132, v120, v132
	v_mul_f32_e32 v120, 0xbfb8aa3b, v121
	v_exp_f32_e32 v120, v120
	v_and_b32_e32 v133, 0xffff0000, v181
	v_mul_f32_e32 v127, v127, v133
	v_and_b32_e32 v133, 0xffff0000, v182
	v_add_f32_e32 v120, 1.0, v120
	v_rcp_f32_e32 v120, v120
	v_mul_f32_e32 v124, v124, v136
	v_and_b32_e32 v121, 0xffff0000, v183
	v_add_f32_e32 v92, 1.0, v92
	v_mul_f32_e32 v133, v120, v133
	v_lshlrev_b32_e32 v120, 16, v183
	v_mul_f32_e32 v134, v122, v120
	v_mul_f32_e32 v120, 0xbfb8aa3b, v123
	v_exp_f32_e32 v120, v120
	v_rcp_f32_e32 v92, v92
	v_pk_add_f32 v[80:81], v[80:81], v[20:21]
	v_exp_f32_e32 v85, v85
	v_add_f32_e32 v120, 1.0, v120
	v_rcp_f32_e32 v120, v120
	v_mul_f32_e32 v86, 0xbfb8aa3b, v86
	v_exp_f32_e32 v86, v86
	v_mul_f32_e32 v80, 0xbfb8aa3b, v80
	v_mul_f32_e32 v123, v120, v121
	v_cvt_pk_bf16_f32 v120, v124, v125
	v_lshlrev_b64 v[124:125], 12, v[130:131]
	v_lshl_add_u64 v[124:125], s[10:11], 0, v[124:125]
	v_lshl_add_u64 v[124:125], v[124:125], 0, v[154:155]
	v_cvt_pk_bf16_f32 v121, v126, v127
	v_cvt_pk_bf16_f32 v122, v132, v133
	v_cvt_pk_bf16_f32 v123, v134, v123
	global_store_dwordx4 v[124:125], v[120:123], off offset:2048
	v_exp_f32_e32 v80, v80
	v_add_f32_e32 v85, 1.0, v85
	v_rcp_f32_e32 v85, v85
	v_add_f32_e32 v86, 1.0, v86
	v_rcp_f32_e32 v86, v86
	v_add_f32_e32 v80, 1.0, v80
	v_rcp_f32_e32 v80, v80
	v_mul_f32_e32 v87, 0xbfb8aa3b, v87
	v_pk_add_f32 v[82:83], v[82:83], v[22:23]
	v_exp_f32_e32 v87, v87
	v_mul_f32_e32 v82, 0xbfb8aa3b, v82
	v_exp_f32_e32 v82, v82
	v_mul_f32_e32 v84, 0xbfb8aa3b, v84
	v_add_f32_e32 v87, 1.0, v87
	v_rcp_f32_e32 v87, v87
	v_add_f32_e32 v82, 1.0, v82
	v_rcp_f32_e32 v82, v82
	v_exp_f32_e32 v84, v84
	v_pk_add_f32 v[76:77], v[76:77], v[36:37]
	v_pk_add_f32 v[78:79], v[78:79], v[38:39]
	v_mul_f32_e32 v77, 0xbfb8aa3b, v77
	v_add_f32_e32 v84, 1.0, v84
	v_rcp_f32_e32 v84, v84
	v_pk_add_f32 v[72:73], v[72:73], v[32:33]
	v_exp_f32_e32 v77, v77
	v_mul_f32_e32 v78, 0xbfb8aa3b, v78
	v_exp_f32_e32 v78, v78
	v_mul_f32_e32 v72, 0xbfb8aa3b, v72
	v_exp_f32_e32 v72, v72
	v_add_f32_e32 v77, 1.0, v77
	v_rcp_f32_e32 v77, v77
	v_add_f32_e32 v78, 1.0, v78
	v_rcp_f32_e32 v78, v78
	v_add_f32_e32 v72, 1.0, v72
	v_rcp_f32_e32 v72, v72
	v_mul_f32_e32 v79, 0xbfb8aa3b, v79
	v_pk_add_f32 v[74:75], v[74:75], v[34:35]
	v_exp_f32_e32 v79, v79
	v_mul_f32_e32 v74, 0xbfb8aa3b, v74
	v_exp_f32_e32 v74, v74
	v_mul_f32_e32 v76, 0xbfb8aa3b, v76
	v_add_f32_e32 v79, 1.0, v79
	v_rcp_f32_e32 v79, v79
	v_add_f32_e32 v74, 1.0, v74
	v_rcp_f32_e32 v74, v74
	v_exp_f32_e32 v76, v76
	v_pk_add_f32 v[68:69], v[68:69], v[16:17]
	v_pk_add_f32 v[70:71], v[70:71], v[18:19]
	v_mul_f32_e32 v69, 0xbfb8aa3b, v69
	v_add_f32_e32 v76, 1.0, v76
	v_rcp_f32_e32 v76, v76
	v_pk_add_f32 v[64:65], v[64:65], v[20:21]
	v_exp_f32_e32 v69, v69
	v_mul_f32_e32 v70, 0xbfb8aa3b, v70
	v_exp_f32_e32 v70, v70
	v_mul_f32_e32 v64, 0xbfb8aa3b, v64
	v_exp_f32_e32 v64, v64
	v_add_f32_e32 v69, 1.0, v69
	v_rcp_f32_e32 v69, v69
	v_add_f32_e32 v70, 1.0, v70
	v_rcp_f32_e32 v70, v70
	v_add_f32_e32 v64, 1.0, v64
	v_rcp_f32_e32 v64, v64
	v_mul_f32_e32 v71, 0xbfb8aa3b, v71
	v_pk_add_f32 v[66:67], v[66:67], v[22:23]
	v_exp_f32_e32 v71, v71
	v_mul_f32_e32 v66, 0xbfb8aa3b, v66
	v_exp_f32_e32 v66, v66
	v_mul_f32_e32 v68, 0xbfb8aa3b, v68
	v_add_f32_e32 v71, 1.0, v71
	v_rcp_f32_e32 v71, v71
	v_add_f32_e32 v66, 1.0, v66
	v_rcp_f32_e32 v66, v66
	v_exp_f32_e32 v68, v68
	v_pk_add_f32 v[60:61], v[60:61], v[36:37]
	v_pk_add_f32 v[62:63], v[62:63], v[38:39]
	v_mul_f32_e32 v61, 0xbfb8aa3b, v61
	v_add_f32_e32 v68, 1.0, v68
	v_rcp_f32_e32 v68, v68
	s_waitcnt vmcnt(15)
	v_lshlrev_b32_e32 v126, 16, v184
	v_and_b32_e32 v120, 0xffff0000, v184
	v_mul_f32_e32 v117, v117, v120
	v_lshlrev_b32_e32 v120, 16, v185
	v_mul_f32_e32 v118, v118, v120
	v_lshlrev_b32_e32 v120, 16, v186
	v_mul_f32_e32 v120, v112, v120
	v_mul_f32_e32 v112, 0xbfb8aa3b, v113
	v_exp_f32_e32 v112, v112
	v_and_b32_e32 v121, 0xffff0000, v185
	v_mul_f32_e32 v119, v119, v121
	v_and_b32_e32 v121, 0xffff0000, v186
	v_add_f32_e32 v112, 1.0, v112
	v_rcp_f32_e32 v112, v112
	v_and_b32_e32 v113, 0xffff0000, v187
	v_mul_f32_e32 v116, v116, v126
	v_pk_add_f32 v[56:57], v[56:57], v[32:33]
	v_mul_f32_e32 v121, v112, v121
	v_lshlrev_b32_e32 v112, 16, v187
	v_mul_f32_e32 v122, v114, v112
	v_mul_f32_e32 v112, 0xbfb8aa3b, v115
	v_exp_f32_e32 v112, v112
	v_exp_f32_e32 v61, v61
	v_mul_f32_e32 v62, 0xbfb8aa3b, v62
	v_exp_f32_e32 v62, v62
	v_add_f32_e32 v112, 1.0, v112
	v_rcp_f32_e32 v112, v112
	v_mul_f32_e32 v56, 0xbfb8aa3b, v56
	v_exp_f32_e32 v56, v56
	v_add_f32_e32 v61, 1.0, v61
	v_mul_f32_e32 v115, v112, v113
	v_cvt_pk_bf16_f32 v112, v116, v117
	v_cvt_pk_bf16_f32 v113, v118, v119
	v_cvt_pk_bf16_f32 v114, v120, v121
	v_cvt_pk_bf16_f32 v115, v122, v115
	global_store_dwordx4 v[124:125], v[112:115], off offset:2304
	v_rcp_f32_e32 v61, v61
	v_add_f32_e32 v62, 1.0, v62
	v_or_b32_e32 v114, 32, v156
	v_ashrrev_i32_e32 v115, 31, v114
	v_lshlrev_b64 v[112:113], 10, v[114:115]
	v_lshl_add_u64 v[112:113], s[8:9], 0, v[112:113]
	v_lshl_add_u64 v[112:113], v[112:113], 0, v[154:155]
	v_rcp_f32_e32 v62, v62
	v_add_f32_e32 v56, 1.0, v56
	v_rcp_f32_e32 v56, v56
	v_mul_f32_e32 v63, 0xbfb8aa3b, v63
	v_pk_add_f32 v[58:59], v[58:59], v[34:35]
	v_exp_f32_e32 v63, v63
	v_mul_f32_e32 v58, 0xbfb8aa3b, v58
	v_exp_f32_e32 v58, v58
	v_mul_f32_e32 v60, 0xbfb8aa3b, v60
	v_add_f32_e32 v63, 1.0, v63
	v_rcp_f32_e32 v63, v63
	v_add_f32_e32 v58, 1.0, v58
	v_rcp_f32_e32 v58, v58
	v_exp_f32_e32 v60, v60
	v_pk_add_f32 v[52:53], v[52:53], v[16:17]
	v_pk_add_f32 v[54:55], v[54:55], v[18:19]
	v_mul_f32_e32 v53, 0xbfb8aa3b, v53
	v_add_f32_e32 v60, 1.0, v60
	v_rcp_f32_e32 v60, v60
	v_pk_add_f32 v[48:49], v[48:49], v[20:21]
	v_exp_f32_e32 v53, v53
	v_mul_f32_e32 v54, 0xbfb8aa3b, v54
	v_exp_f32_e32 v54, v54
	v_mul_f32_e32 v48, 0xbfb8aa3b, v48
	v_exp_f32_e32 v48, v48
	v_add_f32_e32 v53, 1.0, v53
	v_rcp_f32_e32 v53, v53
	v_add_f32_e32 v54, 1.0, v54
	v_rcp_f32_e32 v54, v54
	v_add_f32_e32 v48, 1.0, v48
	v_rcp_f32_e32 v48, v48
	v_mul_f32_e32 v55, 0xbfb8aa3b, v55
	v_pk_add_f32 v[50:51], v[50:51], v[22:23]
	v_exp_f32_e32 v55, v55
	v_mul_f32_e32 v50, 0xbfb8aa3b, v50
	v_exp_f32_e32 v50, v50
	v_mul_f32_e32 v52, 0xbfb8aa3b, v52
	v_add_f32_e32 v55, 1.0, v55
	v_rcp_f32_e32 v55, v55
	v_add_f32_e32 v50, 1.0, v50
	v_rcp_f32_e32 v50, v50
	v_exp_f32_e32 v52, v52
	v_pk_add_f32 v[44:45], v[44:45], v[36:37]
	v_pk_add_f32 v[46:47], v[46:47], v[38:39]
	v_mul_f32_e32 v45, 0xbfb8aa3b, v45
	v_add_f32_e32 v52, 1.0, v52
	v_rcp_f32_e32 v52, v52
	v_pk_add_f32 v[40:41], v[40:41], v[32:33]
	v_exp_f32_e32 v45, v45
	v_mul_f32_e32 v46, 0xbfb8aa3b, v46
	v_exp_f32_e32 v46, v46
	v_mul_f32_e32 v40, 0xbfb8aa3b, v40
	v_exp_f32_e32 v40, v40
	v_add_f32_e32 v45, 1.0, v45
	v_rcp_f32_e32 v45, v45
	v_add_f32_e32 v46, 1.0, v46
	v_rcp_f32_e32 v46, v46
	v_add_f32_e32 v40, 1.0, v40
	v_rcp_f32_e32 v40, v40
	v_mul_f32_e32 v47, 0xbfb8aa3b, v47
	v_pk_add_f32 v[42:43], v[42:43], v[34:35]
	v_exp_f32_e32 v47, v47
	v_mul_f32_e32 v42, 0xbfb8aa3b, v42
	v_exp_f32_e32 v42, v42
	v_mul_f32_e32 v44, 0xbfb8aa3b, v44
	v_add_f32_e32 v47, 1.0, v47
	v_rcp_f32_e32 v47, v47
	v_add_f32_e32 v42, 1.0, v42
	v_rcp_f32_e32 v42, v42
	v_exp_f32_e32 v44, v44
	v_pk_add_f32 v[28:29], v[28:29], v[16:17]
	v_pk_add_f32 v[30:31], v[30:31], v[18:19]
	v_mul_f32_e32 v29, 0xbfb8aa3b, v29
	v_add_f32_e32 v44, 1.0, v44
	v_rcp_f32_e32 v44, v44
	v_pk_add_f32 v[24:25], v[24:25], v[20:21]
	v_exp_f32_e32 v29, v29
	v_mul_f32_e32 v30, 0xbfb8aa3b, v30
	v_exp_f32_e32 v30, v30
	s_waitcnt vmcnt(15)
	v_lshlrev_b32_e32 v120, 16, v188
	v_and_b32_e32 v116, 0xffff0000, v188
	v_mul_f32_e32 v109, v109, v116
	v_lshlrev_b32_e32 v116, 16, v189
	v_mul_f32_e32 v110, v110, v116
	v_lshlrev_b32_e32 v116, 16, v190
	v_mul_f32_e32 v116, v104, v116
	v_mul_f32_e32 v104, 0xbfb8aa3b, v105
	v_exp_f32_e32 v104, v104
	v_and_b32_e32 v117, 0xffff0000, v189
	v_mul_f32_e32 v111, v111, v117
	v_and_b32_e32 v117, 0xffff0000, v190
	v_add_f32_e32 v104, 1.0, v104
	v_rcp_f32_e32 v104, v104
	v_mul_f32_e32 v108, v108, v120
	v_and_b32_e32 v105, 0xffff0000, v191
	v_mul_f32_e32 v24, 0xbfb8aa3b, v24
	v_mul_f32_e32 v117, v104, v117
	v_lshlrev_b32_e32 v104, 16, v191
	v_mul_f32_e32 v118, v106, v104
	v_mul_f32_e32 v104, 0xbfb8aa3b, v107
	v_exp_f32_e32 v104, v104
	v_exp_f32_e32 v24, v24
	v_add_f32_e32 v29, 1.0, v29
	v_rcp_f32_e32 v29, v29
	v_add_f32_e32 v104, 1.0, v104
	v_rcp_f32_e32 v104, v104
	v_add_f32_e32 v30, 1.0, v30
	v_rcp_f32_e32 v30, v30
	v_add_f32_e32 v24, 1.0, v24
	v_mul_f32_e32 v107, v104, v105
	v_cvt_pk_bf16_f32 v104, v108, v109
	v_lshlrev_b64 v[108:109], 12, v[114:115]
	v_lshl_add_u64 v[108:109], s[10:11], 0, v[108:109]
	v_lshl_add_u64 v[108:109], v[108:109], 0, v[154:155]
	v_cvt_pk_bf16_f32 v105, v110, v111
	v_cvt_pk_bf16_f32 v106, v116, v117
	v_cvt_pk_bf16_f32 v107, v118, v107
	global_store_dwordx4 v[108:109], v[104:107], off offset:2048
	v_rcp_f32_e32 v24, v24
	v_mul_f32_e32 v31, 0xbfb8aa3b, v31
	v_pk_add_f32 v[26:27], v[26:27], v[22:23]
	v_exp_f32_e32 v31, v31
	v_mul_f32_e32 v26, 0xbfb8aa3b, v26
	v_exp_f32_e32 v26, v26
	v_mul_f32_e32 v28, 0xbfb8aa3b, v28
	v_add_f32_e32 v31, 1.0, v31
	v_rcp_f32_e32 v31, v31
	v_add_f32_e32 v26, 1.0, v26
	v_rcp_f32_e32 v26, v26
	v_exp_f32_e32 v28, v28
	v_pk_add_f32 v[12:13], v[12:13], v[36:37]
	v_pk_add_f32 v[14:15], v[14:15], v[38:39]
	v_mul_f32_e32 v13, 0xbfb8aa3b, v13
	v_add_f32_e32 v28, 1.0, v28
	v_rcp_f32_e32 v28, v28
	v_pk_add_f32 v[8:9], v[8:9], v[32:33]
	v_exp_f32_e32 v13, v13
	v_mul_f32_e32 v14, 0xbfb8aa3b, v14
	v_exp_f32_e32 v14, v14
	v_mul_f32_e32 v8, 0xbfb8aa3b, v8
	v_exp_f32_e32 v8, v8
	v_add_f32_e32 v13, 1.0, v13
	v_rcp_f32_e32 v13, v13
	v_add_f32_e32 v14, 1.0, v14
	v_rcp_f32_e32 v14, v14
	v_add_f32_e32 v8, 1.0, v8
	v_rcp_f32_e32 v8, v8
	v_mul_f32_e32 v15, 0xbfb8aa3b, v15
	v_pk_add_f32 v[10:11], v[10:11], v[34:35]
	v_exp_f32_e32 v15, v15
	v_mul_f32_e32 v10, 0xbfb8aa3b, v10
	v_exp_f32_e32 v10, v10
	v_mul_f32_e32 v12, 0xbfb8aa3b, v12
	v_add_f32_e32 v15, 1.0, v15
	v_rcp_f32_e32 v15, v15
	v_add_f32_e32 v10, 1.0, v10
	v_rcp_f32_e32 v10, v10
	v_exp_f32_e32 v12, v12
	v_pk_add_f32 v[4:5], v[4:5], v[20:21]
	v_pk_add_f32 v[2:3], v[2:3], v[18:19]
	v_mul_f32_e32 v4, 0xbfb8aa3b, v4
	v_add_f32_e32 v12, 1.0, v12
	v_rcp_f32_e32 v12, v12
	v_exp_f32_e32 v4, v4
	v_pk_add_f32 v[0:1], v[0:1], v[16:17]
	v_mul_f32_e32 v2, 0xbfb8aa3b, v2
	v_pk_add_f32 v[6:7], v[6:7], v[22:23]
	v_mul_f32_e32 v3, 0xbfb8aa3b, v3
	v_exp_f32_e32 v2, v2
	v_mul_f32_e32 v1, 0xbfb8aa3b, v1
	v_mul_f32_e32 v0, 0xbfb8aa3b, v0
	v_mul_f32_e32 v5, 0xbfb8aa3b, v5
	v_exp_f32_e32 v3, v3
	v_exp_f32_e32 v1, v1
	v_exp_f32_e32 v0, v0
	v_mul_f32_e32 v6, 0xbfb8aa3b, v6
	v_mul_f32_e32 v7, 0xbfb8aa3b, v7
	v_exp_f32_e32 v5, v5
	v_exp_f32_e32 v6, v6
	v_exp_f32_e32 v7, v7
	v_add_f32_e32 v4, 1.0, v4
	v_rcp_f32_e32 v4, v4
	v_add_f32_e32 v2, 1.0, v2
	v_add_f32_e32 v3, 1.0, v3
	v_rcp_f32_e32 v2, v2
	v_add_f32_e32 v1, 1.0, v1
	v_add_f32_e32 v0, 1.0, v0
	v_add_f32_e32 v5, 1.0, v5
	v_rcp_f32_e32 v3, v3
	v_rcp_f32_e32 v1, v1
	v_rcp_f32_e32 v0, v0
	v_add_f32_e32 v6, 1.0, v6
	v_add_f32_e32 v7, 1.0, v7
	v_rcp_f32_e32 v5, v5
	v_rcp_f32_e32 v6, v6
	v_rcp_f32_e32 v7, v7
	s_waitcnt vmcnt(15)
	v_lshlrev_b32_e32 v110, 16, v192
	v_and_b32_e32 v104, 0xffff0000, v192
	v_mul_f32_e32 v101, v101, v104
	v_lshlrev_b32_e32 v104, 16, v193
	v_mul_f32_e32 v102, v102, v104
	v_lshlrev_b32_e32 v104, 16, v194
	v_mul_f32_e32 v104, v96, v104
	v_mul_f32_e32 v96, 0xbfb8aa3b, v97
	v_exp_f32_e32 v96, v96
	v_and_b32_e32 v105, 0xffff0000, v193
	v_mul_f32_e32 v103, v103, v105
	v_and_b32_e32 v105, 0xffff0000, v194
	v_add_f32_e32 v96, 1.0, v96
	v_rcp_f32_e32 v96, v96
	v_and_b32_e32 v97, 0xffff0000, v195
	v_mul_f32_e32 v100, v100, v110
	v_mul_f32_e32 v105, v96, v105
	v_lshlrev_b32_e32 v96, 16, v195
	v_mul_f32_e32 v106, v98, v96
	v_mul_f32_e32 v96, 0xbfb8aa3b, v99
	v_exp_f32_e32 v96, v96
	s_nop 0
	v_add_f32_e32 v96, 1.0, v96
	v_rcp_f32_e32 v96, v96
	s_nop 0
	v_mul_f32_e32 v99, v96, v97
	v_cvt_pk_bf16_f32 v96, v100, v101
	v_cvt_pk_bf16_f32 v97, v102, v103
	v_cvt_pk_bf16_f32 v98, v104, v105
	v_cvt_pk_bf16_f32 v99, v106, v99
	global_store_dwordx4 v[108:109], v[96:99], off offset:2304
	s_nop 1
	v_or_b32_e32 v98, 48, v156
	v_ashrrev_i32_e32 v99, 31, v98
	v_lshlrev_b64 v[96:97], 10, v[98:99]
	v_lshl_add_u64 v[96:97], s[8:9], 0, v[96:97]
	v_lshl_add_u64 v[96:97], v[96:97], 0, v[154:155]
	s_waitcnt vmcnt(15)
	v_lshlrev_b32_e32 v104, 16, v196
	v_and_b32_e32 v100, 0xffff0000, v196
	v_mul_f32_e32 v93, v93, v100
	v_lshlrev_b32_e32 v100, 16, v197
	v_mul_f32_e32 v94, v94, v100
	v_lshlrev_b32_e32 v100, 16, v198
	v_mul_f32_e32 v100, v88, v100
	v_mul_f32_e32 v88, 0xbfb8aa3b, v89
	v_exp_f32_e32 v88, v88
	v_and_b32_e32 v101, 0xffff0000, v197
	v_mul_f32_e32 v95, v95, v101
	v_and_b32_e32 v101, 0xffff0000, v198
	v_add_f32_e32 v88, 1.0, v88
	v_rcp_f32_e32 v88, v88
	v_mul_f32_e32 v92, v92, v104
	v_and_b32_e32 v89, 0xffff0000, v199
	v_mul_f32_e32 v101, v88, v101
	v_lshlrev_b32_e32 v88, 16, v199
	v_mul_f32_e32 v102, v90, v88
	v_mul_f32_e32 v88, 0xbfb8aa3b, v91
	v_exp_f32_e32 v88, v88
	s_nop 0
	v_add_f32_e32 v88, 1.0, v88
	v_rcp_f32_e32 v88, v88
	s_nop 0
	v_mul_f32_e32 v91, v88, v89
	v_cvt_pk_bf16_f32 v88, v92, v93
	v_lshlrev_b64 v[92:93], 12, v[98:99]
	v_lshl_add_u64 v[92:93], s[10:11], 0, v[92:93]
	v_lshl_add_u64 v[92:93], v[92:93], 0, v[154:155]
	v_cvt_pk_bf16_f32 v89, v94, v95
	v_cvt_pk_bf16_f32 v90, v100, v101
	v_cvt_pk_bf16_f32 v91, v102, v91
	global_store_dwordx4 v[92:93], v[88:91], off offset:2048
	s_waitcnt vmcnt(15)
	v_lshlrev_b32_e32 v94, 16, v200
	v_and_b32_e32 v88, 0xffff0000, v200
	v_mul_f32_e32 v85, v85, v88
	v_lshlrev_b32_e32 v88, 16, v201
	v_mul_f32_e32 v86, v86, v88
	v_lshlrev_b32_e32 v88, 16, v202
	v_mul_f32_e32 v88, v80, v88
	v_mul_f32_e32 v80, 0xbfb8aa3b, v81
	v_exp_f32_e32 v80, v80
	v_and_b32_e32 v89, 0xffff0000, v201
	v_mul_f32_e32 v87, v87, v89
	v_and_b32_e32 v89, 0xffff0000, v202
	v_add_f32_e32 v80, 1.0, v80
	v_rcp_f32_e32 v80, v80
	v_and_b32_e32 v81, 0xffff0000, v203
	v_mul_f32_e32 v84, v84, v94
	v_mul_f32_e32 v89, v80, v89
	v_lshlrev_b32_e32 v80, 16, v203
	v_mul_f32_e32 v90, v82, v80
	v_mul_f32_e32 v80, 0xbfb8aa3b, v83
	v_exp_f32_e32 v80, v80
	s_nop 0
	v_add_f32_e32 v80, 1.0, v80
	v_rcp_f32_e32 v80, v80
	s_nop 0
	v_mul_f32_e32 v83, v80, v81
	v_cvt_pk_bf16_f32 v80, v84, v85
	v_cvt_pk_bf16_f32 v81, v86, v87
	v_cvt_pk_bf16_f32 v82, v88, v89
	v_cvt_pk_bf16_f32 v83, v90, v83
	global_store_dwordx4 v[92:93], v[80:83], off offset:2304
	s_nop 1
	v_add_u32_e32 v82, 0x80, v156
	v_ashrrev_i32_e32 v83, 31, v82
	v_lshlrev_b64 v[80:81], 10, v[82:83]
	v_lshl_add_u64 v[80:81], s[8:9], 0, v[80:81]
	v_lshl_add_u64 v[80:81], v[80:81], 0, v[154:155]
	s_waitcnt vmcnt(15)
	v_lshlrev_b32_e32 v88, 16, v204
	v_and_b32_e32 v84, 0xffff0000, v204
	v_mul_f32_e32 v77, v77, v84
	v_lshlrev_b32_e32 v84, 16, v205
	v_mul_f32_e32 v78, v78, v84
	v_lshlrev_b32_e32 v84, 16, v206
	v_mul_f32_e32 v84, v72, v84
	v_mul_f32_e32 v72, 0xbfb8aa3b, v73
	v_exp_f32_e32 v72, v72
	v_and_b32_e32 v85, 0xffff0000, v205
	v_mul_f32_e32 v79, v79, v85
	v_and_b32_e32 v85, 0xffff0000, v206
	v_add_f32_e32 v72, 1.0, v72
	v_rcp_f32_e32 v72, v72
	v_mul_f32_e32 v76, v76, v88
	v_and_b32_e32 v73, 0xffff0000, v207
	v_mul_f32_e32 v85, v72, v85
	v_lshlrev_b32_e32 v72, 16, v207
	v_mul_f32_e32 v86, v74, v72
	v_mul_f32_e32 v72, 0xbfb8aa3b, v75
	v_exp_f32_e32 v72, v72
	s_nop 0
	v_add_f32_e32 v72, 1.0, v72
	v_rcp_f32_e32 v72, v72
	s_nop 0
	v_mul_f32_e32 v75, v72, v73
	v_cvt_pk_bf16_f32 v72, v76, v77
	v_lshlrev_b64 v[76:77], 12, v[82:83]
	v_lshl_add_u64 v[76:77], s[10:11], 0, v[76:77]
	v_lshl_add_u64 v[76:77], v[76:77], 0, v[154:155]
	v_cvt_pk_bf16_f32 v73, v78, v79
	v_cvt_pk_bf16_f32 v74, v84, v85
	v_cvt_pk_bf16_f32 v75, v86, v75
	global_store_dwordx4 v[76:77], v[72:75], off offset:2048
	s_waitcnt vmcnt(15)
	v_lshlrev_b32_e32 v78, 16, v208
	v_and_b32_e32 v72, 0xffff0000, v208
	v_mul_f32_e32 v69, v69, v72
	v_lshlrev_b32_e32 v72, 16, v209
	v_mul_f32_e32 v70, v70, v72
	v_lshlrev_b32_e32 v72, 16, v210
	v_mul_f32_e32 v72, v64, v72
	v_mul_f32_e32 v64, 0xbfb8aa3b, v65
	v_exp_f32_e32 v64, v64
	v_and_b32_e32 v73, 0xffff0000, v209
	v_mul_f32_e32 v71, v71, v73
	v_and_b32_e32 v73, 0xffff0000, v210
	v_add_f32_e32 v64, 1.0, v64
	v_rcp_f32_e32 v64, v64
	v_and_b32_e32 v65, 0xffff0000, v211
	v_mul_f32_e32 v68, v68, v78
	v_mul_f32_e32 v73, v64, v73
	v_lshlrev_b32_e32 v64, 16, v211
	v_mul_f32_e32 v74, v66, v64
	v_mul_f32_e32 v64, 0xbfb8aa3b, v67
	v_exp_f32_e32 v64, v64
	s_nop 0
	v_add_f32_e32 v64, 1.0, v64
	v_rcp_f32_e32 v64, v64
	s_nop 0
	v_mul_f32_e32 v67, v64, v65
	v_cvt_pk_bf16_f32 v64, v68, v69
	v_cvt_pk_bf16_f32 v65, v70, v71
	v_cvt_pk_bf16_f32 v66, v72, v73
	v_cvt_pk_bf16_f32 v67, v74, v67
	global_store_dwordx4 v[76:77], v[64:67], off offset:2304
	s_nop 1
	v_add_u32_e32 v66, 0x90, v156
	v_ashrrev_i32_e32 v67, 31, v66
	v_lshlrev_b64 v[64:65], 10, v[66:67]
	v_lshl_add_u64 v[64:65], s[8:9], 0, v[64:65]
	v_lshl_add_u64 v[64:65], v[64:65], 0, v[154:155]
	s_waitcnt vmcnt(15)
	v_lshlrev_b32_e32 v72, 16, v212
	v_and_b32_e32 v68, 0xffff0000, v212
	v_mul_f32_e32 v61, v61, v68
	v_lshlrev_b32_e32 v68, 16, v213
	v_mul_f32_e32 v62, v62, v68
	v_lshlrev_b32_e32 v68, 16, v214
	v_mul_f32_e32 v68, v56, v68
	v_mul_f32_e32 v56, 0xbfb8aa3b, v57
	v_exp_f32_e32 v56, v56
	v_and_b32_e32 v69, 0xffff0000, v213
	v_mul_f32_e32 v63, v63, v69
	v_and_b32_e32 v69, 0xffff0000, v214
	v_add_f32_e32 v56, 1.0, v56
	v_rcp_f32_e32 v56, v56
	v_mul_f32_e32 v60, v60, v72
	v_and_b32_e32 v57, 0xffff0000, v215
	v_mul_f32_e32 v69, v56, v69
	v_lshlrev_b32_e32 v56, 16, v215
	v_mul_f32_e32 v70, v58, v56
	v_mul_f32_e32 v56, 0xbfb8aa3b, v59
	v_exp_f32_e32 v56, v56
	s_nop 0
	v_add_f32_e32 v56, 1.0, v56
	v_rcp_f32_e32 v56, v56
	s_nop 0
	v_mul_f32_e32 v59, v56, v57
	v_cvt_pk_bf16_f32 v56, v60, v61
	v_lshlrev_b64 v[60:61], 12, v[66:67]
	v_lshl_add_u64 v[60:61], s[10:11], 0, v[60:61]
	v_lshl_add_u64 v[60:61], v[60:61], 0, v[154:155]
	v_cvt_pk_bf16_f32 v57, v62, v63
	v_cvt_pk_bf16_f32 v58, v68, v69
	v_cvt_pk_bf16_f32 v59, v70, v59
	global_store_dwordx4 v[60:61], v[56:59], off offset:2048
	s_waitcnt vmcnt(15)
	v_lshlrev_b32_e32 v62, 16, v218
	v_and_b32_e32 v56, 0xffff0000, v218
	v_mul_f32_e32 v53, v53, v56
	v_lshlrev_b32_e32 v56, 16, v219
	v_mul_f32_e32 v54, v54, v56
	v_lshlrev_b32_e32 v56, 16, v220
	v_mul_f32_e32 v56, v48, v56
	v_mul_f32_e32 v48, 0xbfb8aa3b, v49
	v_exp_f32_e32 v48, v48
	v_and_b32_e32 v57, 0xffff0000, v219
	v_mul_f32_e32 v55, v55, v57
	v_and_b32_e32 v57, 0xffff0000, v220
	v_add_f32_e32 v48, 1.0, v48
	v_rcp_f32_e32 v48, v48
	v_and_b32_e32 v49, 0xffff0000, v221
	v_mul_f32_e32 v52, v52, v62
	v_mul_f32_e32 v57, v48, v57
	v_lshlrev_b32_e32 v48, 16, v221
	v_mul_f32_e32 v58, v50, v48
	v_mul_f32_e32 v48, 0xbfb8aa3b, v51
	v_exp_f32_e32 v48, v48
	s_nop 0
	v_add_f32_e32 v48, 1.0, v48
	v_rcp_f32_e32 v48, v48
	s_nop 0
	v_mul_f32_e32 v51, v48, v49
	v_cvt_pk_bf16_f32 v48, v52, v53
	v_cvt_pk_bf16_f32 v49, v54, v55
	v_cvt_pk_bf16_f32 v50, v56, v57
	v_cvt_pk_bf16_f32 v51, v58, v51
	global_store_dwordx4 v[60:61], v[48:51], off offset:2304
	s_nop 1
	v_add_u32_e32 v50, 0xa0, v156
	v_ashrrev_i32_e32 v51, 31, v50
	v_lshlrev_b64 v[48:49], 10, v[50:51]
	v_lshl_add_u64 v[48:49], s[8:9], 0, v[48:49]
	v_lshl_add_u64 v[48:49], v[48:49], 0, v[154:155]
	s_waitcnt vmcnt(15)
	v_lshlrev_b32_e32 v56, 16, v222
	v_and_b32_e32 v52, 0xffff0000, v222
	v_mul_f32_e32 v45, v45, v52
	v_lshlrev_b32_e32 v52, 16, v223
	v_mul_f32_e32 v46, v46, v52
	v_lshlrev_b32_e32 v52, 16, v224
	v_mul_f32_e32 v52, v40, v52
	v_mul_f32_e32 v40, 0xbfb8aa3b, v41
	v_exp_f32_e32 v40, v40
	v_and_b32_e32 v53, 0xffff0000, v223
	v_mul_f32_e32 v47, v47, v53
	v_and_b32_e32 v53, 0xffff0000, v224
	v_add_f32_e32 v40, 1.0, v40
	v_rcp_f32_e32 v40, v40
	v_mul_f32_e32 v44, v44, v56
	v_and_b32_e32 v41, 0xffff0000, v225
	v_mul_f32_e32 v53, v40, v53
	v_lshlrev_b32_e32 v40, 16, v225
	v_mul_f32_e32 v54, v42, v40
	v_mul_f32_e32 v40, 0xbfb8aa3b, v43
	v_exp_f32_e32 v40, v40
	s_nop 0
	v_add_f32_e32 v40, 1.0, v40
	v_rcp_f32_e32 v40, v40
	s_nop 0
	v_mul_f32_e32 v43, v40, v41
	v_cvt_pk_bf16_f32 v40, v44, v45
	v_lshlrev_b64 v[44:45], 12, v[50:51]
	v_lshl_add_u64 v[44:45], s[10:11], 0, v[44:45]
	v_lshl_add_u64 v[44:45], v[44:45], 0, v[154:155]
	v_cvt_pk_bf16_f32 v41, v46, v47
	v_cvt_pk_bf16_f32 v42, v52, v53
	v_cvt_pk_bf16_f32 v43, v54, v43
	global_store_dwordx4 v[44:45], v[40:43], off offset:2048
	s_waitcnt vmcnt(15)
	v_lshlrev_b32_e32 v46, 16, v226
	v_and_b32_e32 v40, 0xffff0000, v226
	v_mul_f32_e32 v29, v29, v40
	v_lshlrev_b32_e32 v40, 16, v227
	v_mul_f32_e32 v30, v30, v40
	v_lshlrev_b32_e32 v40, 16, v228
	v_mul_f32_e32 v40, v24, v40
	v_mul_f32_e32 v24, 0xbfb8aa3b, v25
	v_exp_f32_e32 v24, v24
	v_and_b32_e32 v41, 0xffff0000, v227
	v_mul_f32_e32 v31, v31, v41
	v_and_b32_e32 v41, 0xffff0000, v228
	v_add_f32_e32 v24, 1.0, v24
	v_rcp_f32_e32 v24, v24
	v_and_b32_e32 v25, 0xffff0000, v229
	v_mul_f32_e32 v28, v28, v46
	v_mul_f32_e32 v41, v24, v41
	v_lshlrev_b32_e32 v24, 16, v229
	v_mul_f32_e32 v42, v26, v24
	v_mul_f32_e32 v24, 0xbfb8aa3b, v27
	v_exp_f32_e32 v24, v24
	s_nop 0
	v_add_f32_e32 v24, 1.0, v24
	v_rcp_f32_e32 v24, v24
	s_nop 0
	v_mul_f32_e32 v27, v24, v25
	v_cvt_pk_bf16_f32 v24, v28, v29
	v_cvt_pk_bf16_f32 v25, v30, v31
	v_cvt_pk_bf16_f32 v26, v40, v41
	v_cvt_pk_bf16_f32 v27, v42, v27
	global_store_dwordx4 v[44:45], v[24:27], off offset:2304
	s_nop 1
	v_add_u32_e32 v26, 0xb0, v156
	v_ashrrev_i32_e32 v27, 31, v26
	v_lshlrev_b64 v[24:25], 10, v[26:27]
	v_lshl_add_u64 v[24:25], s[8:9], 0, v[24:25]
	v_lshl_add_u64 v[24:25], v[24:25], 0, v[154:155]
	s_waitcnt vmcnt(15)
	v_lshlrev_b32_e32 v32, 16, v242
	v_and_b32_e32 v28, 0xffff0000, v242
	v_mul_f32_e32 v13, v13, v28
	v_lshlrev_b32_e32 v28, 16, v243
	v_mul_f32_e32 v14, v14, v28
	v_lshlrev_b32_e32 v28, 16, v244
	v_mul_f32_e32 v28, v8, v28
	v_mul_f32_e32 v8, 0xbfb8aa3b, v9
	v_exp_f32_e32 v8, v8
	v_and_b32_e32 v29, 0xffff0000, v243
	v_mul_f32_e32 v15, v15, v29
	v_and_b32_e32 v29, 0xffff0000, v244
	v_add_f32_e32 v8, 1.0, v8
	v_rcp_f32_e32 v8, v8
	v_mul_f32_e32 v12, v12, v32
	v_and_b32_e32 v9, 0xffff0000, v245
	v_mul_f32_e32 v29, v8, v29
	v_lshlrev_b32_e32 v8, 16, v245
	v_mul_f32_e32 v30, v10, v8
	v_mul_f32_e32 v8, 0xbfb8aa3b, v11
	v_exp_f32_e32 v8, v8
	s_nop 0
	v_add_f32_e32 v8, 1.0, v8
	v_rcp_f32_e32 v8, v8
	s_nop 0
	v_mul_f32_e32 v11, v8, v9
	v_cvt_pk_bf16_f32 v8, v12, v13
	v_lshlrev_b64 v[12:13], 12, v[26:27]
	v_lshl_add_u64 v[12:13], s[10:11], 0, v[12:13]
	v_lshl_add_u64 v[12:13], v[12:13], 0, v[154:155]
	v_cvt_pk_bf16_f32 v9, v14, v15
	v_cvt_pk_bf16_f32 v10, v28, v29
	v_cvt_pk_bf16_f32 v11, v30, v11
	global_store_dwordx4 v[12:13], v[8:11], off offset:2048
	s_waitcnt vmcnt(15)
	v_and_b32_e32 v15, 0xffff0000, v252
	v_lshlrev_b32_e32 v10, 16, v252
	v_mul_f32_e32 v4, v4, v10
	v_and_b32_e32 v10, 0xffff0000, v251
	v_lshlrev_b32_e32 v9, 16, v251
	v_mul_f32_e32 v2, v2, v9
	v_and_b32_e32 v9, 0xffff0000, v250
	v_lshlrev_b32_e32 v8, 16, v250
	v_and_b32_e32 v14, 0xffff0000, v253
	v_lshlrev_b32_e32 v11, 16, v253
	v_mul_f32_e32 v3, v3, v10
	v_mul_f32_e32 v1, v1, v9
	v_mul_f32_e32 v0, v0, v8
	v_mul_f32_e32 v5, v5, v15
	v_mul_f32_e32 v6, v6, v11
	v_mul_f32_e32 v7, v7, v14
	v_cvt_pk_bf16_f32 v0, v0, v1
	v_cvt_pk_bf16_f32 v1, v2, v3
	v_cvt_pk_bf16_f32 v2, v4, v5
	v_cvt_pk_bf16_f32 v3, v6, v7
	global_store_dwordx4 v[12:13], v[0:3], off offset:2304
	s_cbranch_vccnz .LBB0_1508
	s_and_b64 vcc, exec, s[2:3]
	s_cbranch_vccnz .LBB0_1507
	s_barrier
	s_branch .LBB0_1507
